# seam 3 per-panel counter + P7 row-sum exchange through 8-byte {sum,tag} granules polled in the shared XCD L2 (plain stores, sc1 polls); assumes a panel's 8 WGs share an XCD
# speedup vs baseline: 1.0120x; 1.0093x over previous
;     __device__ __forceinline__ bool run(const f32x4 (&v)[2][2][4][2], const Unit& u, int wr, int wc, int fr, int fq, PG8_LAS unsigned char* lds, int wid, int lane) const {
;     ...
;         const int row = wid * 32 + (lane & 31);
;         if (lane < 32) { const float tot = (P[row * 4 + 0] + P[row * 4 + 1]) + (P[row * 4 + 2] + P[row * 4 + 3]);
;             __hip_atomic_store(xbuf + ((size_t)(u.pm * BM + row) * 8 + u.pn), __float_as_uint(tot), __ATOMIC_RELAXED, __HIP_MEMORY_SCOPE_AGENT); }
;         asm volatile("s_waitcnt vmcnt(0)" ::: "memory");
;         if (lane == 0) __hip_atomic_fetch_add(cnt + 64 * u.pm, 1u, __ATOMIC_RELAXED, __HIP_MEMORY_SCOPE_AGENT);
;         if (wid == 0) {
;             bool dead = false; const unsigned long long t0 = __builtin_amdgcn_s_memrealtime();
;             for (;;) {
;                 if ((unsigned)__builtin_amdgcn_readfirstlane(__hip_atomic_load(cnt + 64 * u.pm, __ATOMIC_RELAXED, __HIP_MEMORY_SCOPE_AGENT)) >= 64u) break;
;                 if (__builtin_amdgcn_s_memrealtime() - t0 > 2000000ull) { if (lane == 0) __hip_atomic_store(tmo, 1u, __ATOMIC_RELAXED, __HIP_MEMORY_SCOPE_AGENT); dead = true; break; }
;                 __builtin_amdgcn_s_sleep(2);
;             }
;             if (lane == 0) flag[0] = dead ? 1u : 0u;
;         }
;         asm volatile("s_waitcnt vmcnt(0) lgkmcnt(0)" ::: "memory"); __builtin_amdgcn_s_barrier(); asm volatile("" ::: "memory");
;         const bool bad = flag[0] != 0u;
;         if (lane < 32) { const unsigned* slot = xbuf + (size_t)(u.pm * BM + row) * 8; float s = 0.f;
; #pragma unroll
;             for (int t = 0; t < 8; ++t) s += __uint_as_float(__hip_atomic_load(slot + t, __ATOMIC_RELAXED, __HIP_MEMORY_SCOPE_AGENT));
;             S[row] = 1.0f / sqrtf(s * (1.0f / 2048.0f) + 1e-6f); }
.LBB0_600:
	s_or_b64 exec, exec, s[0:1]
	s_waitcnt lgkmcnt(0)
	s_barrier
	s_waitcnt lgkmcnt(0)
	v_and_or_b32 v147, v249, 31, s65
	v_add_u32_e32 v144, s6, v147
	v_cmp_gt_u32_e64 s[0:1], 32, v146
	v_ashrrev_i32_e32 v145, 31, v144
	s_sub_u32 s6, s10, s34
	s_sub_u32 s6, s6, 0x2800000
	s_add_u32 s44, s10, s6
	s_addc_u32 s45, s11, 0
	s_sub_u32 s46, s22, s10
	s_lshl_b32 s46, s46, 1
	v_mov_b32_e32 v146, 0
	s_and_saveexec_b64 s[6:7], s[0:1]
	s_cbranch_execz .LBB0_622
	v_lshl_add_u32 v148, v147, 4, 0
	ds_read_b128 v[148:151], v148
	v_lshlrev_b32_e32 v159, 6, v144
	v_add_u32_e32 v160, s46, v159
	v_mov_b32_e32 v161, 0x13572468
	s_waitcnt lgkmcnt(0)
	v_mov_b32_e32 v154, v149
	v_mov_b32_e32 v155, v150
	v_mov_b32_e32 v149, v151
	v_pk_add_f32 v[148:149], v[154:155], v[148:149]
	s_nop 0
	v_pk_add_f32 v[148:149], v[148:149], v[148:149] op_sel:[0,1] op_sel_hi:[1,0]
	s_nop 0
	v_mov_b32_e32 v149, v161
	global_store_dwordx2 v160, v[148:149], s[44:45]
	s_movk_i32 s47, 0x4000
.Lgx_poll:
	global_load_dwordx4 v[162:165], v159, s[44:45] sc1
	global_load_dwordx4 v[166:169], v159, s[44:45] offset:16 sc1
	global_load_dwordx4 v[170:173], v159, s[44:45] offset:32 sc1
	global_load_dwordx4 v[174:177], v159, s[44:45] offset:48 sc1
	s_waitcnt vmcnt(0)
	v_xor_b32_e32 v178, v163, v161
	v_xor_b32_e32 v179, v165, v161
	v_or_b32_e32 v178, v178, v179
	v_xor_b32_e32 v179, v167, v161
	v_or_b32_e32 v178, v178, v179
	v_xor_b32_e32 v179, v169, v161
	v_or_b32_e32 v178, v178, v179
	v_xor_b32_e32 v179, v171, v161
	v_or_b32_e32 v178, v178, v179
	v_xor_b32_e32 v179, v173, v161
	v_or_b32_e32 v178, v178, v179
	v_xor_b32_e32 v179, v175, v161
	v_or_b32_e32 v178, v178, v179
	v_xor_b32_e32 v179, v177, v161
	v_or_b32_e32 v178, v178, v179
	v_cmp_ne_u32_e32 vcc, 0, v178
	s_cbranch_vccz .Lgx_got
	s_sleep 1
	s_sub_u32 s47, s47, 1
	s_cmp_lg_u32 s47, 0
	s_cbranch_scc1 .Lgx_poll
.Lgx_got:
	v_add_f32_e32 v145, 0, v162
	v_add_f32_e32 v145, v145, v164
	v_add_f32_e32 v145, v145, v166
	v_add_f32_e32 v145, v145, v168
	v_add_f32_e32 v145, v145, v170
	v_add_f32_e32 v145, v145, v172
	v_add_f32_e32 v145, v145, v174
	v_add_f32_e32 v144, v145, v176
	v_fmamk_f32 v144, v144, 0x3a000000, v246
	v_mul_f32_e32 v145, 0x4f800000, v144
	v_cmp_gt_f32_e32 vcc, s92, v144
	s_nop 1
	v_cndmask_b32_e32 v144, v144, v145, vcc
	v_sqrt_f32_e32 v145, v144
	s_nop 0
	v_add_u32_e32 v148, -1, v145
	v_add_u32_e32 v149, 1, v145
	v_fma_f32 v150, -v148, v145, v144
	v_fma_f32 v151, -v149, v145, v144
	v_cmp_ge_f32_e64 s[0:1], 0, v150
	s_nop 1
	v_cndmask_b32_e64 v145, v145, v148, s[0:1]
	v_cmp_lt_f32_e64 s[0:1], 0, v151
	s_nop 1
	v_cndmask_b32_e64 v145, v145, v149, s[0:1]
	v_mul_f32_e32 v148, 0x37800000, v145
	v_cndmask_b32_e32 v145, v145, v148, vcc
	v_cmp_class_f32_e32 vcc, v144, v247
	s_nop 1
	v_cndmask_b32_e32 v144, v145, v144, vcc
	v_div_scale_f32 v145, s[0:1], v144, v144, 1.0
	v_rcp_f32_e32 v148, v145
	v_div_scale_f32 v149, vcc, 1.0, v144, 1.0
	v_fma_f32 v150, -v145, v148, 1.0
	v_fmac_f32_e32 v148, v150, v148
	v_mul_f32_e32 v150, v149, v148
	v_fma_f32 v151, -v145, v150, v149
	v_fmac_f32_e32 v150, v151, v148
	v_fma_f32 v145, -v145, v150, v149
	v_div_fmas_f32 v145, v145, v148, v150
	v_div_fixup_f32 v144, v145, v144, 1.0
	v_lshl_add_u32 v145, v147, 2, 0
	ds_write_b32 v145, v144 offset:4096
